# attnA: P-pack cvts moved under MFMA shadows of the next step
# speedup vs baseline: 1.0133x; 1.0018x over previous
; #define FLAS __attribute__((address_space(3)))
; #define FA_SB() __builtin_amdgcn_sched_barrier(0)
; __device__ __forceinline__ float fadd_s(float a, float b) { float r; asm("v_add_f32_e32 %0, %1, %2" : "=v"(r) : "v"(a), "v"(b)); return r; }
; #define FA_PVM(G) do { o[(G) & 3] = __builtin_amdgcn_mfma_f32_32x32x16_bf16(__builtin_bit_cast(bf16x8, vr[(G) % 3]), __builtin_bit_cast(bf16x8, PWC[(G) >> 2]), o[(G) & 3], 0, 0, 0); if ((G) + 3 < 16) vr[(G) % 3] = FA_VFRAG((G) + 3); } while (0)
; __device__ __forceinline__ void attn_unit_a(FLAS unsigned char* lds, const Unit u) {
;     ...
;     const f32x16 z16 = {0.f,0.f,0.f,0.f,0.f,0.f,0.f,0.f,0.f,0.f,0.f,0.f,0.f,0.f,0.f,0.f};
;     f32x16 o[NDB];
; #pragma unroll
;     for (int i = 0; i < NDB; ++i) o[i] = z16;
;     float mrun = 0.f, lsum = 0.f, fpend = 1.f; bool first = true, pend = false;
;     ...
;     f32x16 pa0, pa1, pb0, pb1; float cbC = 0.f;
;     { bool zi; FA_BIAS(0, pa0, pa1, cbC, zi); if (zi) { pa0 = z16; pa1 = z16; }
;       const FLAS unsigned char* kb = lds + LA_K;
; #pragma unroll
;       for (int d0 = 0; d0 < 4; ++d0) { const int ko = (2 * d0 + hi) * 1024 + ((r32 ^ (2 * d0 + hi)) * 16); const bf16x8 a0 = *(const FLAS bf16x8*)(kb + ko), a1 = *(const FLAS bf16x8*)(kb + ko + 512);
;           pa0 = __builtin_amdgcn_mfma_f32_32x32x16_bf16(a0, qr[d0], pa0, 0, 0, 0); pa1 = __builtin_amdgcn_mfma_f32_32x32x16_bf16(a1, qr[d0], pa1, 0, 0, 0); } }
;     u32x4 pwa[4] = {{0u,0u,0u,0u},{0u,0u,0u,0u},{0u,0u,0u,0u},{0u,0u,0u,0u}}, pwb[4] = {{0u,0u,0u,0u},{0u,0u,0u,0u},{0u,0u,0u,0u},{0u,0u,0u,0u}};
;     ...
;         const float off = cbC - mrun;
;         FA_SB();
;         float ra, rb, rm;
;         FA_PVM(0); pC0[0] = fadd_s(pC0[0], off); pC1[0] = fadd_s(pC1[0], off); pC0[1] = fadd_s(pC0[1], off); pC1[1] = fadd_s(pC1[1], off); pC0[2] = fadd_s(pC0[2], off); pC1[2] = fadd_s(pC1[2], off); FA_SB();
.LBB0_432:
	v_xor_b32_e32 v1, v243, v5
	v_lshlrev_b32_e32 v1, 4, v1
	v_lshl_add_u32 v4, v243, 10, 0
	v_add_u32_e32 v247, v4, v1
	ds_read_b128 v[6:9], v247
	ds_read_b128 v[10:13], v247 offset:512
	v_or_b32_e32 v1, 2, v243
	v_bitop3_b32 v4, v243, v5, 2 bitop3:0x36
	v_lshlrev_b32_e32 v4, 4, v4
	v_lshl_add_u32 v1, v1, 10, 0
	v_add_u32_e32 v248, v1, v4
	s_waitcnt lgkmcnt(1)
	v_mfma_f32_32x32x16_bf16 v[128:143], v[6:9], v[160:163], v[128:143]
	ds_read_b128 v[6:9], v248
	v_or_b32_e32 v1, 4, v243
	v_bitop3_b32 v4, v243, v5, 4 bitop3:0x36
	v_lshlrev_b32_e32 v4, 4, v4
	v_lshl_add_u32 v1, v1, 10, 0
	v_add_u32_e32 v249, v1, v4
	s_lshr_b32 s0, s43, 8
	s_waitcnt lgkmcnt(1)
	v_mfma_f32_32x32x16_bf16 v[144:159], v[10:13], v[160:163], v[144:159]
	ds_read_b128 v[10:13], v248 offset:512
	s_lshl_b32 s15, s41, 1
	s_and_b32 s18, s40, 15
	s_and_b32 s0, s0, 1
	s_lshl_b32 s26, s42, 7
	s_bfe_u32 s1, s41, 0x2000d
	s_and_b32 s15, s15, 0xc000
	s_waitcnt lgkmcnt(1)
	v_mfma_f32_32x32x16_bf16 v[128:143], v[6:9], v[164:167], v[128:143]
	ds_read_b128 v[6:9], v249
	s_lshl_b32 s18, s18, 8
	s_lshl_b32 s20, s0, 7
	s_add_i32 s0, 0, 0x16000
	v_add_u32_e32 v240, s0, v224
	s_add_u32 s0, s70, s15
	s_mul_i32 s19, s1, 0x1800000
	s_waitcnt lgkmcnt(1)
	v_mfma_f32_32x32x16_bf16 v[144:159], v[10:13], v[164:167], v[144:159]
	ds_read_b128 v[10:13], v249 offset:512
	s_addc_u32 s1, s71, 0
	v_or_b32_e32 v1, 6, v243
	v_bitop3_b32 v4, v243, v5, 6 bitop3:0x36
	s_add_u32 s0, s0, s12
	v_lshlrev_b32_e32 v4, 4, v4
	v_lshl_add_u32 v1, v1, 10, 0
	s_waitcnt lgkmcnt(1)
	v_mfma_f32_32x32x16_bf16 v[128:143], v[6:9], v[168:171], v[128:143]
	s_addc_u32 s1, s1, 0
	v_add_u32_e32 v250, v1, v4
	v_lshl_add_u64 v[228:229], s[0:1], 0, v[2:3]
	s_lshl_b32 s0, s5, 8
	ds_read_b128 v[6:9], v250
	ds_read_b128 v[14:17], v250 offset:512
	s_and_b32 s0, s0, 0xfffff000
	s_or_b32 s0, s0, s18
	s_waitcnt lgkmcnt(2)
	v_mfma_f32_32x32x16_bf16 v[144:159], v[10:13], v[168:171], v[144:159]
	s_add_i32 s0, s0, s14
	s_sub_i32 s48, 64, s0
	v_add_lshl_u32 v1, s0, v5, 2
	s_add_u32 s0, s70, s20
	s_addc_u32 s1, s71, 0
	s_add_u32 s0, s0, s4
	s_addc_u32 s1, s1, 0
	s_waitcnt lgkmcnt(1)
	v_mfma_f32_32x32x16_bf16 v[128:143], v[6:9], v[172:175], v[128:143]
	s_add_u32 s0, s0, s19
	s_addc_u32 s1, s1, 0
	v_sub_u32_e32 v1, v224, v1
	v_mov_b64_e32 v[2:3], s[0:1]
	v_mul_u32_u24_e32 v246, 0x90, v5
	v_add_u32_e32 v210, 0, v1
	v_mad_i64_i32 v[230:231], s[0:1], v0, s65, v[2:3]
	s_waitcnt lgkmcnt(0)
	v_mfma_f32_32x32x16_bf16 v[144:159], v[14:17], v[172:175], v[144:159]
	v_mov_b32_e32 v14, v209
	v_mov_b32_e32 v15, v209
	v_mov_b32_e32 v0, v209
	v_mov_b32_e32 v1, v209
	v_mov_b32_e32 v2, v209
	v_mov_b32_e32 v3, v209
	v_mov_b32_e32 v4, v209
	v_mov_b32_e32 v5, v209
	v_mov_b32_e32 v6, v209
	v_mov_b32_e32 v7, v209
	v_mov_b32_e32 v8, v209
	v_mov_b32_e32 v9, v209
	v_mov_b32_e32 v10, v209
	v_mov_b32_e32 v11, v209
	v_mov_b32_e32 v12, v209
	v_mov_b32_e32 v13, v209
	v_mov_b32_e32 v188, 0
	v_mov_b64_e32 v[30:31], v[14:15]
	v_mov_b64_e32 v[46:47], v[14:15]
	v_mov_b64_e32 v[62:63], v[14:15]
	v_ashrrev_i32_e32 v223, 31, v222
	v_add3_u32 v251, 0, v246, v224
	s_mov_b32 s49, 0
	s_mov_b64 s[24:25], -1
	v_mov_b32_e32 v211, 0
	v_mov_b32_e32 v226, 1.0
	v_mov_b64_e32 v[28:29], v[12:13]
	v_mov_b64_e32 v[26:27], v[10:11]
	v_mov_b64_e32 v[24:25], v[8:9]
	v_mov_b64_e32 v[22:23], v[6:7]
	v_mov_b64_e32 v[20:21], v[4:5]
	v_mov_b64_e32 v[18:19], v[2:3]
	v_mov_b64_e32 v[16:17], v[0:1]
	v_mov_b64_e32 v[44:45], v[12:13]
	v_mov_b64_e32 v[42:43], v[10:11]
	v_mov_b64_e32 v[40:41], v[8:9]
	v_mov_b64_e32 v[38:39], v[6:7]
	v_mov_b64_e32 v[36:37], v[4:5]
	v_mov_b64_e32 v[34:35], v[2:3]
	v_mov_b64_e32 v[32:33], v[0:1]
	v_mov_b64_e32 v[60:61], v[12:13]
	v_mov_b64_e32 v[58:59], v[10:11]
	v_mov_b64_e32 v[56:57], v[8:9]
	v_mov_b64_e32 v[54:55], v[6:7]
	v_mov_b64_e32 v[52:53], v[4:5]
	v_mov_b64_e32 v[50:51], v[2:3]
	v_mov_b64_e32 v[48:49], v[0:1]
	s_mov_b32 s19, 0
	v_mov_b32_e32 v212, 0
	v_mov_b32_e32 v189, v188
	v_mov_b32_e32 v190, v188
	v_mov_b32_e32 v191, v188
	v_mov_b32_e32 v192, v188
	v_mov_b32_e32 v193, v188
	v_mov_b32_e32 v194, v188
	v_mov_b32_e32 v195, v188
	v_mov_b32_e32 v196, v188
	v_mov_b32_e32 v197, v188
	v_mov_b32_e32 v198, v188
	v_mov_b32_e32 v199, v188
	v_mov_b32_e32 v104, v188
	v_mov_b32_e32 v105, v188
	v_mov_b32_e32 v106, v188
	v_mov_b32_e32 v107, v188
	s_waitcnt lgkmcnt(0)
	v_readlane_b32 s100, v254, 47
	v_mov_b32_e32 v92, s13
	s_nop 3
	v_mov_b32_e32 v93, s100
	ds_read_b32 v92, v92
	ds_read_b32 v93, v93
	v_sub_f32_e32 v94, v204, v211
	v_add_f32_e32 v96, v128, v94
	v_add_f32_e32 v112, v144, v94
	v_add_f32_e32 v97, v129, v94
	v_add_f32_e32 v113, v145, v94
	v_add_f32_e32 v98, v130, v94
	v_add_f32_e32 v114, v146, v94
	v_add_f32_e32 v99, v131, v94
	v_add_f32_e32 v115, v147, v94
	v_add_f32_e32 v100, v132, v94
	v_add_f32_e32 v116, v148, v94
	v_add_f32_e32 v101, v133, v94
	v_add_f32_e32 v117, v149, v94
	v_add_f32_e32 v102, v134, v94
	v_add_f32_e32 v118, v150, v94
	v_add_f32_e32 v103, v135, v94
	v_add_f32_e32 v119, v151, v94
	v_add_f32_e32 v104, v136, v94
	v_add_f32_e32 v120, v152, v94
	v_add_f32_e32 v105, v137, v94
	v_add_f32_e32 v121, v153, v94
	v_add_f32_e32 v106, v138, v94
	v_add_f32_e32 v122, v154, v94
	v_add_f32_e32 v107, v139, v94
	v_add_f32_e32 v123, v155, v94
	v_add_f32_e32 v108, v140, v94
	v_add_f32_e32 v124, v156, v94
	v_add_f32_e32 v109, v141, v94
	v_add_f32_e32 v125, v157, v94
	v_add_f32_e32 v110, v142, v94
	v_add_f32_e32 v126, v158, v94
	v_add_f32_e32 v111, v143, v94
	v_add_f32_e32 v127, v159, v94
	v_mov_b32_e32 v144, 0x7fc00000
	v_mov_b32_e32 v145, 0x7fc00000
	v_mov_b32_e32 v146, 0x7fc00000
	v_mov_b32_e32 v147, 0x7fc00000
	v_mov_b32_e32 v148, 0x7fc00000
	v_mov_b32_e32 v149, 0x7fc00000
	v_mov_b32_e32 v150, 0x7fc00000
	v_mov_b32_e32 v151, 0x7fc00000
	v_mov_b32_e32 v152, 0x7fc00000
	v_mov_b32_e32 v153, 0x7fc00000
	v_mov_b32_e32 v154, 0x7fc00000
	v_mov_b32_e32 v155, 0x7fc00000
	v_mov_b32_e32 v156, 0x7fc00000
	v_mov_b32_e32 v157, 0x7fc00000
	v_mov_b32_e32 v158, 0x7fc00000
	v_mov_b32_e32 v159, 0x7fc00000
	v_mov_b32_e32 v204, 0
	v_mov_b32_e32 v205, 0
	v_mov_b32_e32 v206, 0
	v_mov_b32_e32 v207, 0
	s_waitcnt lgkmcnt(0)
	v_readfirstlane_b32 s101, v92
	v_readfirstlane_b32 s100, v93
	v_mov_b32_e32 v72, 0
	v_mov_b32_e32 v73, 0
	v_mov_b32_e32 v74, 0
	v_mov_b32_e32 v75, 0
	v_mov_b32_e32 v76, 0
	v_mov_b32_e32 v77, 0
	v_mov_b32_e32 v78, 0
	v_mov_b32_e32 v79, 0
	v_mov_b32_e32 v80, 0
	v_mov_b32_e32 v81, 0
	v_mov_b32_e32 v82, 0
	v_mov_b32_e32 v83, 0
	v_mov_b32_e32 v84, 0
	v_mov_b32_e32 v85, 0
	v_mov_b32_e32 v86, 0
	v_mov_b32_e32 v87, 0
	v_mov_b32_e32 v88, 0
	v_mov_b32_e32 v89, 0
	v_mov_b32_e32 v90, 0
	v_mov_b32_e32 v91, 0
	v_mov_b32_e32 v92, 0
	v_mov_b32_e32 v93, 0
	v_mov_b32_e32 v94, 0
	v_mov_b32_e32 v95, 0
	s_cbranch_execnz .LBB0_435
	s_branch .LBB0_434

; #define FA_SB() __builtin_amdgcn_sched_barrier(0)
; __device__ __forceinline__ float fadd_s(float a, float b) { float r; asm("v_add_f32_e32 %0, %1, %2" : "=v"(r) : "v"(a), "v"(b)); return r; }
; __device__ __forceinline__ void attn_unit_a(FLAS unsigned char* lds, const Unit u) {
;     ...
;         u32x4 vr[3];
; #pragma unroll
;         for (int m = 0; m < 3; ++m) vr[m] = FA_VFRAG(m);
;         const float off = cbC - mrun;
;         FA_SB();
;         float ra, rb, rm;
;         FA_PVM(0); pC0[0] = fadd_s(pC0[0], off); pC1[0] = fadd_s(pC1[0], off); pC0[1] = fadd_s(pC0[1], off); pC1[1] = fadd_s(pC1[1], off); pC0[2] = fadd_s(pC0[2], off); pC1[2] = fadd_s(pC1[2], off); FA_SB();
;         FA_PVM(1); ra = __builtin_fmaxf(__builtin_fmaxf(pC0[0], pC0[1]), pC0[2]); rb = __builtin_fmaxf(__builtin_fmaxf(pC1[0], pC1[1]), pC1[2]); pC0[3] = fadd_s(pC0[3], off); pC1[3] = fadd_s(pC1[3], off); pC0[4] = fadd_s(pC0[4], off); pC1[4] = fadd_s(pC1[4], off); FA_SB();
;         FA_PVM(2); ra = __builtin_fmaxf(__builtin_fmaxf(ra, pC0[3]), pC0[4]); rb = __builtin_fmaxf(__builtin_fmaxf(rb, pC1[3]), pC1[4]); pC0[5] = fadd_s(pC0[5], off); pC1[5] = fadd_s(pC1[5], off); pC0[6] = fadd_s(pC0[6], off); pC1[6] = fadd_s(pC1[6], off); FA_SB();
;         FA_PVM(3); ra = __builtin_fmaxf(__builtin_fmaxf(ra, pC0[5]), pC0[6]); rb = __builtin_fmaxf(__builtin_fmaxf(rb, pC1[5]), pC1[6]); pC0[7] = fadd_s(pC0[7], off); pC1[7] = fadd_s(pC1[7], off); pC0[8] = fadd_s(pC0[8], off); pC1[8] = fadd_s(pC1[8], off); FA_SB();
;         FA_PVM(4); ra = __builtin_fmaxf(__builtin_fmaxf(ra, pC0[7]), pC0[8]); rb = __builtin_fmaxf(__builtin_fmaxf(rb, pC1[7]), pC1[8]); pC0[9] = fadd_s(pC0[9], off); pC1[9] = fadd_s(pC1[9], off); pC0[10] = fadd_s(pC0[10], off); pC1[10] = fadd_s(pC1[10], off); FA_SB();
;         FA_PVM(5); ra = __builtin_fmaxf(__builtin_fmaxf(ra, pC0[9]), pC0[10]); rb = __builtin_fmaxf(__builtin_fmaxf(rb, pC1[9]), pC1[10]); pC0[11] = fadd_s(pC0[11], off); pC1[11] = fadd_s(pC1[11], off); pC0[12] = fadd_s(pC0[12], off); pC1[12] = fadd_s(pC1[12], off); FA_SB();
;         FA_PVM(6); ra = __builtin_fmaxf(__builtin_fmaxf(ra, pC0[11]), pC0[12]); rb = __builtin_fmaxf(__builtin_fmaxf(rb, pC1[11]), pC1[12]); pC0[13] = fadd_s(pC0[13], off); pC1[13] = fadd_s(pC1[13], off); pC0[14] = fadd_s(pC0[14], off); pC1[14] = fadd_s(pC1[14], off); FA_SB();
.LBB0_437:
	s_add_i32 s12, s19, -1
	s_xor_b64 s[20:21], s[24:25], -1
	s_and_b32 s18, s12, 3
	s_mulk_i32 s18, 0x4800
	s_cmp_lg_u32 s49, 0
	s_cselect_b32 s12, s18, 0
	v_add_u32_e32 v200, s12, v251
	ds_read_b128 v[128:131], v200 offset:16384
	ds_read_b128 v[132:135], v200 offset:20992
	ds_read_b128 v[136:139], v200 offset:25600
	s_waitcnt lgkmcnt(2)
	v_mfma_f32_32x32x16_bf16 v[48:63], v[128:131], v[204:207], v[48:63]
	ds_read_b128 v[128:131], v200 offset:30208
	v_max3_f32 v140, v96, v97, v98
	v_max3_f32 v141, v112, v113, v114
	v_cvt_pk_bf16_f32 v196, v72, v73
	v_cvt_pk_bf16_f32 v197, v74, v75
	s_waitcnt lgkmcnt(2)
	v_mfma_f32_32x32x16_bf16 v[32:47], v[132:135], v[204:207], v[32:47]
	ds_read_b128 v[132:135], v200 offset:16416
	v_max3_f32 v140, v140, v99, v100
	v_max3_f32 v141, v141, v115, v116
	v_cvt_pk_bf16_f32 v198, v76, v77
	v_cvt_pk_bf16_f32 v199, v78, v79
	s_waitcnt lgkmcnt(2)
	v_mfma_f32_32x32x16_bf16 v[16:31], v[136:139], v[204:207], v[16:31]
	ds_read_b128 v[136:139], v200 offset:21024
	v_max3_f32 v140, v140, v101, v102
	v_max3_f32 v141, v141, v117, v118
	v_cvt_pk_bf16_f32 v192, v80, v81
	v_cvt_pk_bf16_f32 v193, v82, v83
	s_waitcnt lgkmcnt(2)
	v_mfma_f32_32x32x16_bf16 v[0:15], v[128:131], v[204:207], v[0:15]
	ds_read_b128 v[128:131], v200 offset:25632
	v_max3_f32 v140, v140, v103, v104
	v_max3_f32 v141, v141, v119, v120
	v_cvt_pk_bf16_f32 v194, v84, v85
	v_cvt_pk_bf16_f32 v195, v86, v87
	s_waitcnt lgkmcnt(2)
	v_mfma_f32_32x32x16_bf16 v[48:63], v[132:135], v[196:199], v[48:63]
	ds_read_b128 v[132:135], v200 offset:30240
	v_max3_f32 v140, v140, v105, v106
	v_max3_f32 v141, v141, v121, v122
	v_cvt_pk_bf16_f32 v188, v88, v89
	v_cvt_pk_bf16_f32 v189, v90, v91
	s_waitcnt lgkmcnt(2)
	v_mfma_f32_32x32x16_bf16 v[32:47], v[136:139], v[196:199], v[32:47]
	ds_read_b128 v[136:139], v200 offset:16448
	v_max3_f32 v140, v140, v107, v108
	v_max3_f32 v141, v141, v123, v124
	v_cvt_pk_bf16_f32 v190, v92, v93
	v_cvt_pk_bf16_f32 v191, v94, v95
	s_waitcnt lgkmcnt(2)
	v_mfma_f32_32x32x16_bf16 v[16:31], v[128:131], v[196:199], v[16:31]
	ds_read_b128 v[128:131], v200 offset:21056
	v_max3_f32 v140, v140, v109, v110
	v_max3_f32 v141, v141, v125, v126
	s_waitcnt lgkmcnt(2)
	v_mfma_f32_32x32x16_bf16 v[0:15], v[132:135], v[196:199], v[0:15]
	ds_read_b128 v[132:135], v200 offset:25664
	v_max3_f32 v140, v140, v141, v111
	v_max_f32_e32 v140, v140, v127
	v_mov_b32_e32 v141, v140
	s_nop 1
	v_permlane32_swap_b32 v140, v141
	s_nop 1
	s_nop 0
	v_max_f32_e32 v140, v140, v141
	s_andn2_b64 vcc, exec, s[20:21]
	s_cbranch_vccnz .LBB0_440
	v_cmp_lt_f32_e32 vcc, s39, v140
	s_cmp_lg_u64 vcc, 0
	s_mov_b32 s12, 0
	s_cselect_b64 s[14:15], -1, 0
	v_mov_b32_e32 v141, v211
	s_andn2_b64 vcc, exec, s[14:15]
	s_cbranch_vccz .LBB0_441

; #define FA_SB() __builtin_amdgcn_sched_barrier(0)
; #define FA_PVM(G) do { o[(G) & 3] = __builtin_amdgcn_mfma_f32_32x32x16_bf16(__builtin_bit_cast(bf16x8, vr[(G) % 3]), __builtin_bit_cast(bf16x8, PWC[(G) >> 2]), o[(G) & 3], 0, 0, 0); if ((G) + 3 < 16) vr[(G) % 3] = FA_VFRAG((G) + 3); } while (0)
; #define FA_EXP2(J, PX, R) do { const float e0_ = __builtin_amdgcn_exp2f(PX[R]), e1_ = __builtin_amdgcn_exp2f(PX[(R) + 1]); ps += e0_; ps += e1_; PWN[(J) >> 2][(J) & 3] = cvtpk(e0_, e1_); } while (0)
; __device__ __forceinline__ void attn_unit_a(FLAS unsigned char* lds, const Unit u) {
;     ...
;         if (first || __any(rm > 8.0f)) {
;             const float dl = __builtin_fmaxf(rm, first ? -1000.0f : 0.0f); const float f = first ? 1.0f : __builtin_amdgcn_exp2f(-dl);
;             mrun = first ? dl : mrun + dl; lsum *= f; fpend = f; pend = !first; first = false;
; #pragma unroll
;             for (int r = 0; r < 16; ++r) { pC0[r] = pC0[r] - dl; pC1[r] = pC1[r] - dl; }
;         }
;         float ps = 0.f;
;         bf16x8 kf[4];
; #pragma unroll
;         for (int g = 8; g < 16; ++g) { FA_PVM(g); FA_EXP2(g - 8, pC0, 2 * (g - 8));
;             if (g == 12) { kf[0] = FA_KF(0, 0); kf[1] = FA_KF(0, 1); kf[2] = FA_KF(1, 0); kf[3] = FA_KF(1, 1); }
;             FA_SB(); }
;         float cbN; bool ziN; const int inx = (i + 1 < NT) ? i + 1 : NT - 1;
;         FA_BIAS(inx, pN0, pN1, cbN, ziN);
;         FA_SB();
;         if (ziN) { pN0 = __builtin_amdgcn_mfma_f32_32x32x16_bf16(kf[0], qr[0], z16, 0, 0, 0); FA_EXP2(8, pC1, 0); FA_SB(); pN1 = __builtin_amdgcn_mfma_f32_32x32x16_bf16(kf[1], qr[0], z16, 0, 0, 0); }
;         else { pN0 = __builtin_amdgcn_mfma_f32_32x32x16_bf16(kf[0], qr[0], pN0, 0, 0, 0); FA_EXP2(8, pC1, 0); FA_SB(); pN1 = __builtin_amdgcn_mfma_f32_32x32x16_bf16(kf[1], qr[0], pN1, 0, 0, 0); }
;         kf[0] = FA_KF(2, 0); kf[1] = FA_KF(2, 1); FA_EXP2(9, pC1, 2); FA_SB();
;         pN0 = __builtin_amdgcn_mfma_f32_32x32x16_bf16(kf[2], qr[1], pN0, 0, 0, 0); FA_EXP2(10, pC1, 4); FA_SB();
.LBB0_440:
	v_bfrev_b32_e32 v141, 1
	s_mov_b32 s12, 0xc47a0000
	s_mov_b64 s[14:15], s[24:25]
	s_andn2_b64 vcc, exec, s[14:15]
	s_cbranch_vccnz .LBB0_439
.LBB0_441:
	v_max_f32_e64 v142, s12, s12
	v_max_f32_e32 v140, v140, v140
	v_max_f32_e32 v140, v140, v142
	v_exp_f32_e64 v142, -v140
	v_add_f32_e32 v211, v141, v140
	v_sub_f32_e32 v111, v111, v140
	v_sub_f32_e32 v110, v110, v140
	v_cndmask_b32_e64 v226, v142, 1.0, s[24:25]
	v_mul_f32_e32 v212, v212, v226
	v_sub_f32_e32 v109, v109, v140
	v_sub_f32_e32 v108, v108, v140
	v_sub_f32_e32 v107, v107, v140
	v_sub_f32_e32 v106, v106, v140
	v_sub_f32_e32 v105, v105, v140
	v_sub_f32_e32 v104, v104, v140
	v_sub_f32_e32 v103, v103, v140
	v_sub_f32_e32 v102, v102, v140
	v_sub_f32_e32 v101, v101, v140
	v_sub_f32_e32 v100, v100, v140
	v_sub_f32_e32 v99, v99, v140
	v_sub_f32_e32 v98, v98, v140
	v_sub_f32_e32 v97, v97, v140
	v_sub_f32_e32 v96, v96, v140
	v_sub_f32_e32 v127, v127, v140
	v_sub_f32_e32 v126, v126, v140
	v_sub_f32_e32 v125, v125, v140
	v_sub_f32_e32 v124, v124, v140
	v_sub_f32_e32 v123, v123, v140
	v_sub_f32_e32 v122, v122, v140
	v_sub_f32_e32 v121, v121, v140
	v_sub_f32_e32 v120, v120, v140
	v_sub_f32_e32 v119, v119, v140
	v_sub_f32_e32 v118, v118, v140
	v_sub_f32_e32 v117, v117, v140
	v_sub_f32_e32 v116, v116, v140
	v_sub_f32_e32 v115, v115, v140
	v_sub_f32_e32 v114, v114, v140
	v_sub_f32_e32 v113, v113, v140
	v_sub_f32_e32 v112, v112, v140
.LBB0_442:
	s_waitcnt lgkmcnt(2)
	v_mfma_f32_32x32x16_bf16 v[48:63], v[136:139], v[192:195], v[48:63]
	ds_read_b128 v[136:139], v200 offset:30272
	v_exp_f32_e32 v96, v96
	v_exp_f32_e32 v97, v97
	s_waitcnt lgkmcnt(2)
	v_mfma_f32_32x32x16_bf16 v[32:47], v[128:131], v[192:195], v[32:47]
	ds_read_b128 v[128:131], v200 offset:16480
	v_exp_f32_e32 v98, v98
	v_exp_f32_e32 v99, v99
	v_add_f32_e32 v212, v96, v212
	v_add_f32_e32 v212, v97, v212
	s_waitcnt lgkmcnt(2)
	v_mfma_f32_32x32x16_bf16 v[16:31], v[132:135], v[192:195], v[16:31]
	ds_read_b128 v[132:135], v200 offset:21088
	v_exp_f32_e32 v100, v100
	v_exp_f32_e32 v101, v101
	v_add_f32_e32 v212, v98, v212
	v_add_f32_e32 v212, v99, v212
	s_waitcnt lgkmcnt(2)
	v_mfma_f32_32x32x16_bf16 v[0:15], v[136:139], v[192:195], v[0:15]
	ds_read_b128 v[136:139], v200 offset:25696
	v_exp_f32_e32 v102, v102
	v_exp_f32_e32 v103, v103
	v_add_f32_e32 v212, v100, v212
	v_add_f32_e32 v212, v101, v212
	s_waitcnt lgkmcnt(2)
	v_mfma_f32_32x32x16_bf16 v[48:63], v[128:131], v[188:191], v[48:63]
	ds_read_b128 v[128:131], v200 offset:30304
	ds_read_b128 v[204:207], v247 offset:8192
	ds_read_b128 v[200:203], v247 offset:8704
	ds_read_b128 v[196:199], v248 offset:8192
	ds_read_b128 v[192:195], v248 offset:8704
	v_exp_f32_e32 v104, v104
	v_exp_f32_e32 v105, v105
	v_add_f32_e32 v212, v102, v212
	v_add_f32_e32 v212, v103, v212
	s_waitcnt lgkmcnt(6)
	v_mfma_f32_32x32x16_bf16 v[32:47], v[132:135], v[188:191], v[32:47]
	v_exp_f32_e32 v106, v106
	v_exp_f32_e32 v107, v107
	v_add_f32_e32 v212, v104, v212
	v_add_f32_e32 v212, v105, v212
	s_waitcnt lgkmcnt(5)
	v_mfma_f32_32x32x16_bf16 v[16:31], v[136:139], v[188:191], v[16:31]
	v_exp_f32_e32 v108, v108
	v_exp_f32_e32 v109, v109
	v_add_f32_e32 v212, v106, v212
	v_add_f32_e32 v212, v107, v212
	s_waitcnt lgkmcnt(4)
	v_mfma_f32_32x32x16_bf16 v[0:15], v[128:131], v[188:191], v[0:15]
	v_exp_f32_e32 v110, v110
	v_exp_f32_e32 v111, v111
	v_add_f32_e32 v212, v108, v212
	v_add_f32_e32 v212, v109, v212
	s_sub_i32 s12, s48, 31
	s_cmpk_lt_i32 s12, 0x22f
	s_cbranch_scc0 .Lz_plus_e
	s_cmpk_gt_i32 s48, 0xfd92
	s_cbranch_scc1 .Lgather_e
	v_sub_f32_e32 v142, s100, v211
	s_branch .Lz_chk_e
.Lz_plus_e:
	v_sub_f32_e32 v142, s101, v211
.Lz_chk_e:
	v_cmp_neq_f32_e32 vcc, v142, v144
	s_cbranch_vccz .Lz_go_e
	v_mov_b32_e32 v144, v142
	v_mov_b32_e32 v145, v142
	v_mov_b32_e32 v146, v142
	v_mov_b32_e32 v147, v142
	v_mov_b32_e32 v148, v142
	v_mov_b32_e32 v149, v142
	v_mov_b32_e32 v150, v142
	v_mov_b32_e32 v151, v142
	v_mov_b32_e32 v152, v142
	v_mov_b32_e32 v153, v142
	v_mov_b32_e32 v154, v142
	v_mov_b32_e32 v155, v142
	v_mov_b32_e32 v156, v142
	v_mov_b32_e32 v157, v142
	v_mov_b32_e32 v158, v142
	v_mov_b32_e32 v159, v142
	s_nop 1

; #define FLAS __attribute__((address_space(3)))
; __device__ __forceinline__ void attn_unit_a(FLAS unsigned char* lds, const Unit u) {
;     ...
;         const int vsp = (i == 0) ? 0 : ((i - 1) & 3);
;         const FLAS unsigned char* vb_ = lds + LA_V + vsp * VBUF + r32 * VPITCH + hi * 16;
;         const FLAS unsigned char* kb = lds + LA_K + ((i + 1) & 1) * KBUF;
;     ...
;         u32x4 vr[3];
; #pragma unroll
;         for (int m = 0; m < 3; ++m) vr[m] = FA_VFRAG(m);
;         const float off = cbC - mrun;
;         FA_SB();
;         float ra, rb, rm;
;         FA_PVM(0); pC0[0] = fadd_s(pC0[0], off); pC1[0] = fadd_s(pC1[0], off); pC0[1] = fadd_s(pC0[1], off); pC1[1] = fadd_s(pC1[1], off); pC0[2] = fadd_s(pC0[2], off); pC1[2] = fadd_s(pC1[2], off); FA_SB();
;         FA_PVM(1); ra = __builtin_fmaxf(__builtin_fmaxf(pC0[0], pC0[1]), pC0[2]); rb = __builtin_fmaxf(__builtin_fmaxf(pC1[0], pC1[1]), pC1[2]); pC0[3] = fadd_s(pC0[3], off); pC1[3] = fadd_s(pC1[3], off); pC0[4] = fadd_s(pC0[4], off); pC1[4] = fadd_s(pC1[4], off); FA_SB();
;         FA_PVM(2); ra = __builtin_fmaxf(__builtin_fmaxf(ra, pC0[3]), pC0[4]); rb = __builtin_fmaxf(__builtin_fmaxf(rb, pC1[3]), pC1[4]); pC0[5] = fadd_s(pC0[5], off); pC1[5] = fadd_s(pC1[5], off); pC0[6] = fadd_s(pC0[6], off); pC1[6] = fadd_s(pC1[6], off); FA_SB();
;         FA_PVM(3); ra = __builtin_fmaxf(__builtin_fmaxf(ra, pC0[5]), pC0[6]); rb = __builtin_fmaxf(__builtin_fmaxf(rb, pC1[5]), pC1[6]); pC0[7] = fadd_s(pC0[7], off); pC1[7] = fadd_s(pC1[7], off); pC0[8] = fadd_s(pC0[8], off); pC1[8] = fadd_s(pC1[8], off); FA_SB();
;         FA_PVM(4); ra = __builtin_fmaxf(__builtin_fmaxf(ra, pC0[7]), pC0[8]); rb = __builtin_fmaxf(__builtin_fmaxf(rb, pC1[7]), pC1[8]); pC0[9] = fadd_s(pC0[9], off); pC1[9] = fadd_s(pC1[9], off); pC0[10] = fadd_s(pC0[10], off); pC1[10] = fadd_s(pC1[10], off); FA_SB();
;         FA_PVM(5); ra = __builtin_fmaxf(__builtin_fmaxf(ra, pC0[9]), pC0[10]); rb = __builtin_fmaxf(__builtin_fmaxf(rb, pC1[9]), pC1[10]); pC0[11] = fadd_s(pC0[11], off); pC1[11] = fadd_s(pC1[11], off); pC0[12] = fadd_s(pC0[12], off); pC1[12] = fadd_s(pC1[12], off); FA_SB();
;         FA_PVM(6); ra = __builtin_fmaxf(__builtin_fmaxf(ra, pC0[11]), pC0[12]); rb = __builtin_fmaxf(__builtin_fmaxf(rb, pC1[11]), pC1[12]); pC0[13] = fadd_s(pC0[13], off); pC1[13] = fadd_s(pC1[13], off); pC0[14] = fadd_s(pC0[14], off); pC1[14] = fadd_s(pC1[14], off); FA_SB();
.LBB0_460:
	s_and_b32 s0, s19, 2
	s_mulk_i32 s0, 0x4800
	v_add_u32_e32 v201, s0, v251
	v_cvt_pk_bf16_f32 v140, v96, v97
	v_cvt_pk_bf16_f32 v141, v98, v99
	v_cvt_pk_bf16_f32 v142, v100, v101
	v_cvt_pk_bf16_f32 v143, v102, v103
	ds_read_b128 v[128:131], v201 offset:16384
	ds_read_b128 v[132:135], v201 offset:20992
	ds_read_b128 v[136:139], v201 offset:25600
	s_waitcnt lgkmcnt(2)
	v_mfma_f32_32x32x16_bf16 v[48:63], v[128:131], v[140:143], v[48:63]
	ds_read_b128 v[128:131], v201 offset:30208
	v_max3_f32 v96, v64, v65, v66
	v_max3_f32 v97, v80, v81, v82
	v_cvt_pk_bf16_f32 v232, v104, v105
	v_cvt_pk_bf16_f32 v233, v106, v107
	s_waitcnt lgkmcnt(2)
	v_mfma_f32_32x32x16_bf16 v[32:47], v[132:135], v[140:143], v[32:47]
	ds_read_b128 v[132:135], v201 offset:16416
	v_max3_f32 v96, v96, v67, v68
	v_max3_f32 v97, v97, v83, v84
	v_cvt_pk_bf16_f32 v234, v108, v109
	v_cvt_pk_bf16_f32 v235, v110, v111
	s_waitcnt lgkmcnt(2)
	v_mfma_f32_32x32x16_bf16 v[16:31], v[136:139], v[140:143], v[16:31]
	ds_read_b128 v[136:139], v201 offset:21024
	v_max3_f32 v96, v96, v69, v70
	v_max3_f32 v97, v97, v85, v86
	s_waitcnt lgkmcnt(2)
	v_mfma_f32_32x32x16_bf16 v[0:15], v[128:131], v[140:143], v[0:15]
	ds_read_b128 v[128:131], v201 offset:25632
	v_max3_f32 v96, v96, v71, v72
	v_max3_f32 v97, v97, v87, v88
	s_waitcnt lgkmcnt(2)
	v_mfma_f32_32x32x16_bf16 v[48:63], v[132:135], v[232:235], v[48:63]
	ds_read_b128 v[132:135], v201 offset:30240
	v_max3_f32 v96, v96, v73, v74
	v_max3_f32 v97, v97, v89, v90
	v_cvt_pk_bf16_f32 v140, v112, v113
	v_cvt_pk_bf16_f32 v141, v114, v115
	s_waitcnt lgkmcnt(2)
	v_mfma_f32_32x32x16_bf16 v[32:47], v[136:139], v[232:235], v[32:47]
	ds_read_b128 v[136:139], v201 offset:16448
	v_max3_f32 v96, v96, v75, v76
	v_max3_f32 v97, v97, v91, v92
	v_cvt_pk_bf16_f32 v142, v116, v117
	v_cvt_pk_bf16_f32 v143, v118, v119
	s_waitcnt lgkmcnt(2)
	v_mfma_f32_32x32x16_bf16 v[16:31], v[128:131], v[232:235], v[16:31]
	ds_read_b128 v[128:131], v201 offset:21056
	v_max3_f32 v96, v96, v77, v78
	v_max3_f32 v97, v97, v93, v94
	s_waitcnt lgkmcnt(2)
	v_mfma_f32_32x32x16_bf16 v[0:15], v[132:135], v[232:235], v[0:15]
	ds_read_b128 v[132:135], v201 offset:25664
	v_max3_f32 v96, v96, v97, v79
	v_max_f32_e32 v96, v96, v95
	v_mov_b32_e32 v97, v96
	s_nop 1
	v_permlane32_swap_b32 v96, v97
	s_nop 1
	s_nop 0
	v_max_f32_e32 v96, v96, v97
	v_cmp_lt_f32_e32 vcc, s39, v96
	s_cmp_lg_u64 vcc, 0
	s_cselect_b64 s[0:1], -1, 0
	s_cbranch_vccz .LBB0_462
	v_max_f32_e32 v96, v96, v96
	v_max_f32_e32 v96, 0, v96
	v_exp_f32_e64 v226, -v96
	v_add_f32_e32 v211, v211, v96
	v_sub_f32_e32 v64, v64, v96
	v_sub_f32_e32 v65, v65, v96
	v_mul_f32_e32 v212, v212, v226
	v_sub_f32_e32 v66, v66, v96
	v_sub_f32_e32 v67, v67, v96
	v_sub_f32_e32 v68, v68, v96
	v_sub_f32_e32 v69, v69, v96
	v_sub_f32_e32 v70, v70, v96
	v_sub_f32_e32 v71, v71, v96
	v_sub_f32_e32 v72, v72, v96
	v_sub_f32_e32 v73, v73, v96
	v_sub_f32_e32 v74, v74, v96
	v_sub_f32_e32 v75, v75, v96
	v_sub_f32_e32 v76, v76, v96
	v_sub_f32_e32 v77, v77, v96
	v_sub_f32_e32 v78, v78, v96
	v_sub_f32_e32 v79, v79, v96
	v_sub_f32_e32 v80, v80, v96
	v_sub_f32_e32 v81, v81, v96
	v_sub_f32_e32 v82, v82, v96
	v_sub_f32_e32 v83, v83, v96
	v_sub_f32_e32 v84, v84, v96
	v_sub_f32_e32 v85, v85, v96
	v_sub_f32_e32 v86, v86, v96
	v_sub_f32_e32 v87, v87, v96
	v_sub_f32_e32 v88, v88, v96
	v_sub_f32_e32 v89, v89, v96
	v_sub_f32_e32 v90, v90, v96
	v_sub_f32_e32 v91, v91, v96
	v_sub_f32_e32 v92, v92, v96
	v_sub_f32_e32 v93, v93, v96
	v_sub_f32_e32 v94, v94, v96
	v_sub_f32_e32 v95, v95, v96
.LBB0_462:
	s_waitcnt lgkmcnt(2)
	v_mfma_f32_32x32x16_bf16 v[48:63], v[136:139], v[140:143], v[48:63]
	ds_read_b128 v[136:139], v201 offset:30272
	v_exp_f32_e32 v64, v64
	v_exp_f32_e32 v65, v65
	v_cvt_pk_bf16_f32 v232, v120, v121
	v_cvt_pk_bf16_f32 v233, v122, v123
	s_waitcnt lgkmcnt(2)
	v_mfma_f32_32x32x16_bf16 v[32:47], v[128:131], v[140:143], v[32:47]
	ds_read_b128 v[128:131], v201 offset:16480
	v_exp_f32_e32 v66, v66
	v_exp_f32_e32 v67, v67
	v_add_f32_e32 v212, v64, v212
	v_add_f32_e32 v212, v65, v212
	v_cvt_pk_bf16_f32 v234, v124, v125
	v_cvt_pk_bf16_f32 v235, v126, v127
	s_waitcnt lgkmcnt(2)
	v_mfma_f32_32x32x16_bf16 v[16:31], v[132:135], v[140:143], v[16:31]
	ds_read_b128 v[132:135], v201 offset:21088
	v_exp_f32_e32 v68, v68
	v_exp_f32_e32 v69, v69
	v_add_f32_e32 v212, v66, v212
	v_add_f32_e32 v212, v67, v212
	s_waitcnt lgkmcnt(2)
	v_mfma_f32_32x32x16_bf16 v[0:15], v[136:139], v[140:143], v[0:15]
	ds_read_b128 v[136:139], v201 offset:25696
	v_exp_f32_e32 v70, v70
	v_exp_f32_e32 v71, v71
	v_add_f32_e32 v212, v68, v212
	v_add_f32_e32 v212, v69, v212
	s_waitcnt lgkmcnt(2)
	v_mfma_f32_32x32x16_bf16 v[48:63], v[128:131], v[232:235], v[48:63]
	ds_read_b128 v[128:131], v201 offset:30304
	ds_read_b128 v[200:203], v247
	ds_read_b128 v[196:199], v247 offset:512
	ds_read_b128 v[192:195], v248
	ds_read_b128 v[188:191], v248 offset:512
	v_exp_f32_e32 v72, v72
	v_exp_f32_e32 v73, v73
	v_add_f32_e32 v212, v70, v212
	v_add_f32_e32 v212, v71, v212
	s_waitcnt lgkmcnt(6)
	v_mfma_f32_32x32x16_bf16 v[32:47], v[132:135], v[232:235], v[32:47]
	v_exp_f32_e32 v74, v74
	v_exp_f32_e32 v75, v75
	v_add_f32_e32 v212, v72, v212
	v_add_f32_e32 v212, v73, v212
	s_waitcnt lgkmcnt(5)
	v_mfma_f32_32x32x16_bf16 v[16:31], v[136:139], v[232:235], v[16:31]
	v_exp_f32_e32 v76, v76
	v_exp_f32_e32 v77, v77
	v_add_f32_e32 v212, v74, v212
	v_add_f32_e32 v212, v75, v212
	s_waitcnt lgkmcnt(4)
	v_mfma_f32_32x32x16_bf16 v[0:15], v[128:131], v[232:235], v[0:15]
	v_exp_f32_e32 v78, v78
	v_exp_f32_e32 v79, v79
	v_add_f32_e32 v212, v76, v212
	v_add_f32_e32 v212, v77, v212
	s_min_u32 s12, s34, 0x7f
	s_lshl_b32 s12, s12, 6
	s_sub_i32 s14, s12, s47
	s_sub_i32 s15, s14, 31
	s_cmpk_lt_i32 s15, 0x22f
	s_cbranch_scc0 .Lz_plus_o
	s_cmpk_gt_i32 s14, 0xfd92
	s_cbranch_scc1 .Lgather_o
	v_sub_f32_e32 v126, s100, v211
	s_branch .Lz_chk_o

; #define FLAS __attribute__((address_space(3)))
; __device__ __forceinline__ float xhalf_sum(float m) { unsigned a = __builtin_bit_cast(unsigned, m), b = a; xswap(a, b); return __builtin_bit_cast(float, a) + __builtin_bit_cast(float, b); }
; __device__ __forceinline__ void attn_unit_a(FLAS unsigned char* lds, const Unit u) {
;     ...
;         if (i + 2 < NT) { *(FLAS u32x4*)(lds + LA_K + (i & 1) * KBUF + kdst) = kreg;
; #pragma unroll
;             for (int j = 0; j < 2; ++j) { *(FLAS u32x2*)(lds + LA_V + ((i + 2) & 3) * VBUF + vdst + j * 64 * VPITCH) = (u32x2){vreg[j].x, vreg[j].y}; *(FLAS u32x2*)(lds + LA_V + ((i + 2) & 3) * VBUF + vdst + j * 64 * VPITCH + 16) = (u32x2){vreg[j].z, vreg[j].w}; } }
;         __syncthreads();
;     };
;     for (int i = 0; i < NT; i += 2) { step(i, pa0, pa1, pb0, pb1, pwa, pwb); if (i + 1 < NT) step(i + 1, pb0, pb1, pa0, pa1, pwb, pwa); }
;     if (pend) {
; #pragma unroll
;         for (int d = 0; d < NDB; ++d) o[d] = o[d] * fpend; }
;     if (NT & 1) { FA_PVP((NT - 1) & 3, pwb); } else { FA_PVP((NT - 1) & 3, pwa); }
;     ...
;     const float inv = 1.0f / xhalf_sum(lsum);
;     bf16_t* op = u.O + (size_t)(u.tok0 + q) * u.ldo + 4 * hi;
;     if (u.comb) {
;         const float lam = *u.lamp, gsc = 1.0f - u.lam_init;
;         const bf16_t* o1p = u.O1 + (size_t)(u.tok0 + q) * 512 + 4 * hi;
.LBB0_476:
	s_mov_b64 s[14:15], 0x100
	v_lshl_add_u64 v[228:229], v[228:229], 0, s[14:15]
	s_mov_b64 s[14:15], 0x60000
	v_cvt_pk_bf16_f32 v206, v68, v69
	v_cvt_pk_bf16_f32 v207, v70, v71
	s_addk_i32 s48, 0x80
	s_addk_i32 s49, 0x200
	v_lshl_add_u64 v[230:231], v[230:231], 0, s[14:15]
	s_mov_b64 s[24:25], 0
	s_and_b64 vcc, exec, s[4:5]
	v_cvt_pk_bf16_f32 v204, v64, v65
	v_cvt_pk_bf16_f32 v205, v66, v67
	s_waitcnt lgkmcnt(0)
	s_barrier
	s_cbranch_vccz .LBB0_433
	s_andn2_b64 vcc, exec, s[0:1]
	s_cbranch_vccnz .LBB0_479
	v_pk_mul_f32 v[62:63], v[62:63], v[226:227] op_sel_hi:[1,0]
	v_pk_mul_f32 v[60:61], v[60:61], v[226:227] op_sel_hi:[1,0]
	v_pk_mul_f32 v[58:59], v[58:59], v[226:227] op_sel_hi:[1,0]
	v_pk_mul_f32 v[56:57], v[56:57], v[226:227] op_sel_hi:[1,0]
	v_pk_mul_f32 v[54:55], v[54:55], v[226:227] op_sel_hi:[1,0]
	v_pk_mul_f32 v[52:53], v[52:53], v[226:227] op_sel_hi:[1,0]
	v_pk_mul_f32 v[50:51], v[50:51], v[226:227] op_sel_hi:[1,0]
	v_pk_mul_f32 v[48:49], v[48:49], v[226:227] op_sel_hi:[1,0]
	v_pk_mul_f32 v[46:47], v[46:47], v[226:227] op_sel_hi:[1,0]
	v_pk_mul_f32 v[44:45], v[44:45], v[226:227] op_sel_hi:[1,0]
	v_pk_mul_f32 v[42:43], v[42:43], v[226:227] op_sel_hi:[1,0]
	v_pk_mul_f32 v[40:41], v[40:41], v[226:227] op_sel_hi:[1,0]
	v_pk_mul_f32 v[38:39], v[38:39], v[226:227] op_sel_hi:[1,0]
	v_pk_mul_f32 v[36:37], v[36:37], v[226:227] op_sel_hi:[1,0]
	v_pk_mul_f32 v[34:35], v[34:35], v[226:227] op_sel_hi:[1,0]
	v_pk_mul_f32 v[32:33], v[32:33], v[226:227] op_sel_hi:[1,0]
	v_pk_mul_f32 v[30:31], v[30:31], v[226:227] op_sel_hi:[1,0]
	v_pk_mul_f32 v[28:29], v[28:29], v[226:227] op_sel_hi:[1,0]
	v_pk_mul_f32 v[26:27], v[26:27], v[226:227] op_sel_hi:[1,0]
	v_pk_mul_f32 v[24:25], v[24:25], v[226:227] op_sel_hi:[1,0]
	v_pk_mul_f32 v[22:23], v[22:23], v[226:227] op_sel_hi:[1,0]
	v_pk_mul_f32 v[20:21], v[20:21], v[226:227] op_sel_hi:[1,0]
	v_pk_mul_f32 v[18:19], v[18:19], v[226:227] op_sel_hi:[1,0]
	v_pk_mul_f32 v[16:17], v[16:17], v[226:227] op_sel_hi:[1,0]
	v_pk_mul_f32 v[14:15], v[14:15], v[226:227] op_sel_hi:[1,0]
	v_pk_mul_f32 v[12:13], v[12:13], v[226:227] op_sel_hi:[1,0]
	v_pk_mul_f32 v[10:11], v[10:11], v[226:227] op_sel_hi:[1,0]
	v_pk_mul_f32 v[8:9], v[8:9], v[226:227] op_sel_hi:[1,0]
	v_pk_mul_f32 v[6:7], v[6:7], v[226:227] op_sel_hi:[1,0]
	v_pk_mul_f32 v[4:5], v[4:5], v[226:227] op_sel_hi:[1,0]
	v_pk_mul_f32 v[2:3], v[2:3], v[226:227] op_sel_hi:[1,0]
	v_pk_mul_f32 v[0:1], v[0:1], v[226:227] op_sel_hi:[1,0]
.LBB0_479:
	v_cvt_pk_bf16_f32 v196, v72, v73
	v_cvt_pk_bf16_f32 v197, v74, v75
	v_cvt_pk_bf16_f32 v198, v76, v77
	v_cvt_pk_bf16_f32 v199, v78, v79
	v_cvt_pk_bf16_f32 v192, v80, v81
	v_cvt_pk_bf16_f32 v193, v82, v83
	v_cvt_pk_bf16_f32 v194, v84, v85
	v_cvt_pk_bf16_f32 v195, v86, v87
	v_cvt_pk_bf16_f32 v188, v88, v89
	v_cvt_pk_bf16_f32 v189, v90, v91
	v_cvt_pk_bf16_f32 v190, v92, v93
	v_cvt_pk_bf16_f32 v191, v94, v95
	v_readlane_b32 s12, v254, 48
	s_lshl_b32 s0, s26, 1
	s_add_u32 s0, s16, s0
	v_add3_u32 v82, s12, v246, v224
	ds_read_b128 v[64:67], v82
	ds_read_b128 v[68:71], v82 offset:4608
	ds_read_b128 v[72:75], v82 offset:9216
	ds_read_b128 v[76:79], v82 offset:13824
	s_addc_u32 s1, s17, 0
	s_cmp_eq_u32 s44, 0
	v_mov_b32_e32 v240, v213
	s_cselect_b32 s4, s0, s45
	s_cselect_b32 s5, s1, s46
	s_movk_i32 s12, 0x200
	s_cselect_b32 s12, s12, 0x600
	s_cmp_lg_u32 s44, 0
	v_mov_b32_e32 v80, s4
	v_mov_b32_e32 v81, s5
	s_waitcnt lgkmcnt(3)
	v_mfma_f32_32x32x16_bf16 v[48:63], v[64:67], v[204:207], v[48:63]
	ds_read_b128 v[64:67], v82 offset:32
	s_waitcnt lgkmcnt(3)
	v_mfma_f32_32x32x16_bf16 v[32:47], v[68:71], v[204:207], v[32:47]
	ds_read_b128 v[68:71], v82 offset:4640
	s_waitcnt lgkmcnt(3)
	v_mfma_f32_32x32x16_bf16 v[16:31], v[72:75], v[204:207], v[16:31]
	ds_read_b128 v[72:75], v82 offset:9248
	s_waitcnt lgkmcnt(3)
	v_mfma_f32_32x32x16_bf16 v[0:15], v[76:79], v[204:207], v[0:15]
	ds_read_b128 v[76:79], v82 offset:13856
	s_waitcnt lgkmcnt(3)
	v_mfma_f32_32x32x16_bf16 v[48:63], v[64:67], v[196:199], v[48:63]
	ds_read_b128 v[64:67], v82 offset:64
	s_waitcnt lgkmcnt(3)
	v_mfma_f32_32x32x16_bf16 v[32:47], v[68:71], v[196:199], v[32:47]
	ds_read_b128 v[68:71], v82 offset:4672
	s_waitcnt lgkmcnt(3)
	v_mfma_f32_32x32x16_bf16 v[16:31], v[72:75], v[196:199], v[16:31]
	ds_read_b128 v[72:75], v82 offset:9280
	s_waitcnt lgkmcnt(3)
	v_mfma_f32_32x32x16_bf16 v[0:15], v[76:79], v[196:199], v[0:15]
	ds_read_b128 v[76:79], v82 offset:13888
	s_waitcnt lgkmcnt(3)
	v_mfma_f32_32x32x16_bf16 v[48:63], v[64:67], v[192:195], v[48:63]
	ds_read_b128 v[64:67], v82 offset:96
	s_waitcnt lgkmcnt(3)
	v_mfma_f32_32x32x16_bf16 v[32:47], v[68:71], v[192:195], v[32:47]
	ds_read_b128 v[68:71], v82 offset:4704
	s_waitcnt lgkmcnt(3)
	v_mfma_f32_32x32x16_bf16 v[16:31], v[72:75], v[192:195], v[16:31]
	ds_read_b128 v[72:75], v82 offset:9312
	s_waitcnt lgkmcnt(3)
	v_mfma_f32_32x32x16_bf16 v[0:15], v[76:79], v[192:195], v[0:15]
	ds_read_b128 v[76:79], v82 offset:13920
	s_waitcnt lgkmcnt(3)
	v_mfma_f32_32x32x16_bf16 v[48:63], v[64:67], v[188:191], v[48:63]
	s_waitcnt lgkmcnt(2)
	v_mfma_f32_32x32x16_bf16 v[32:47], v[68:71], v[188:191], v[32:47]
	s_waitcnt lgkmcnt(1)
	v_mfma_f32_32x32x16_bf16 v[16:31], v[72:75], v[188:191], v[16:31]
	s_waitcnt lgkmcnt(0)
	v_mfma_f32_32x32x16_bf16 v[0:15], v[76:79], v[188:191], v[0:15]
	v_mov_b32_e32 v64, v212
	s_nop 1
	v_permlane32_swap_b32 v212, v64
	s_nop 1
	v_lshlrev_b32_e32 v208, 3, v243
	v_add_f32_e32 v64, v212, v64
	v_div_scale_f32 v65, s[4:5], v64, v64, 1.0
	v_rcp_f32_e32 v66, v65
	v_div_scale_f32 v67, vcc, 1.0, v64, 1.0
	v_mov_b32_e32 v244, v227
	v_fma_f32 v68, -v65, v66, 1.0
	v_fmac_f32_e32 v66, v68, v66
	v_mul_f32_e32 v68, v67, v66
	v_fma_f32 v69, -v65, v68, v67
	v_fmac_f32_e32 v68, v69, v66
	v_fma_f32 v65, -v65, v68, v67
	v_div_fmas_f32 v65, v65, v66, v68
	v_div_fixup_f32 v66, v65, v64, 1.0
	v_mad_i64_i32 v[64:65], s[4:5], s12, v222, 0
	v_lshl_add_u64 v[64:65], v[64:65], 1, v[80:81]
	v_lshl_add_u64 v[64:65], v[64:65], 0, v[208:209]
	s_mov_b64 s[4:5], -1
	s_cbranch_scc0 .LBB0_481
; __device__ __forceinline__ void attn_unit_a(FLAS unsigned char* lds, const Unit u) {
;     ...
;         const float lam = *u.lamp, gsc = 1.0f - u.lam_init;
;         const bf16_t* o1p = u.O1 + (size_t)(u.tok0 + q) * 512 + 4 * hi;
;         float ss = 0.f;
; #pragma unroll
;         for (int db = 0; db < NDB; ++db)
; #pragma unroll
;             for (int g = 0; g < 4; ++g) {
;                 const unsigned long long w = __hip_atomic_load((const unsigned long long*)(o1p + db * 32 + 8 * g), __ATOMIC_RELAXED, __HIP_MEMORY_SCOPE_AGENT);
;                 const unsigned w0 = (unsigned)w, w1 = (unsigned)(w >> 32);
;                 const float a0 = __builtin_bit_cast(float, w0 << 16), a1 = __builtin_bit_cast(float, w0 & 0xffff0000u), a2 = __builtin_bit_cast(float, w1 << 16), a3 = __builtin_bit_cast(float, w1 & 0xffff0000u);
;                 const float x0 = a0 - lam * (o[db][4 * g] * inv), x1 = a1 - lam * (o[db][4 * g + 1] * inv), x2 = a2 - lam * (o[db][4 * g + 2] * inv), x3 = a3 - lam * (o[db][4 * g + 3] * inv);
;                 o[db][4 * g] = x0; o[db][4 * g + 1] = x1; o[db][4 * g + 2] = x2; o[db][4 * g + 3] = x3; ss += (x0 * x0 + x1 * x1) + (x2 * x2 + x3 * x3); }
	v_lshlrev_b32_e32 v67, 2, v243
	v_lshlrev_b64 v[68:69], 10, v[222:223]
	v_lshl_add_u64 v[68:69], s[0:1], 0, v[68:69]
	v_lshlrev_b32_e32 v208, 1, v67
	v_lshl_add_u64 v[68:69], v[68:69], 0, v[208:209]
	global_load_dword v70, v209, s[6:7]
	global_load_dwordx2 v[72:73], v[68:69], off sc1
	global_load_dwordx2 v[74:75], v[68:69], off offset:16 sc1
	global_load_dwordx2 v[76:77], v[68:69], off offset:32 sc1
	global_load_dwordx2 v[78:79], v[68:69], off offset:48 sc1
	global_load_dwordx2 v[80:81], v[68:69], off offset:64 sc1
	global_load_dwordx2 v[82:83], v[68:69], off offset:80 sc1
	global_load_dwordx2 v[84:85], v[68:69], off offset:96 sc1
	global_load_dwordx2 v[86:87], v[68:69], off offset:112 sc1
	global_load_dwordx2 v[88:89], v[68:69], off offset:128 sc1
	global_load_dwordx2 v[90:91], v[68:69], off offset:144 sc1
	global_load_dwordx2 v[92:93], v[68:69], off offset:160 sc1
	global_load_dwordx2 v[94:95], v[68:69], off offset:176 sc1
	global_load_dwordx2 v[96:97], v[68:69], off offset:192 sc1
	global_load_dwordx2 v[98:99], v[68:69], off offset:208 sc1
	global_load_dwordx2 v[100:101], v[68:69], off offset:224 sc1
	s_nop 0
	global_load_dwordx2 v[68:69], v[68:69], off offset:240 sc1
	v_lshlrev_b32_e32 v67, 2, v67
	s_waitcnt vmcnt(15)
	v_lshlrev_b32_e32 v102, 16, v72
	v_and_b32_e32 v103, 0xffff0000, v72
	v_lshlrev_b32_e32 v72, 16, v73
	s_waitcnt vmcnt(12)
	v_lshlrev_b32_e32 v108, 16, v78
	v_and_b32_e32 v109, 0xffff0000, v78
	v_lshlrev_b32_e32 v110, 16, v79
	v_and_b32_e32 v111, 0xffff0000, v79
	v_pk_mul_f32 v[78:79], v[14:15], v[66:67] op_sel_hi:[1,0]
	v_and_b32_e32 v73, 0xffff0000, v73
	s_waitcnt vmcnt(9)
	v_lshlrev_b32_e32 v142, 16, v84
	v_and_b32_e32 v143, 0xffff0000, v84
	v_lshlrev_b32_e32 v144, 16, v85
	v_and_b32_e32 v145, 0xffff0000, v85
	v_lshlrev_b32_e32 v116, 16, v80
	v_and_b32_e32 v117, 0xffff0000, v80
	s_waitcnt vmcnt(0)
	v_lshlrev_b32_e32 v114, 16, v68
	v_and_b32_e32 v115, 0xffff0000, v68
	v_lshlrev_b32_e32 v68, 16, v69
	v_and_b32_e32 v69, 0xffff0000, v69
	v_pk_fma_f32 v[68:69], v[78:79], v[70:71], v[68:69] op_sel_hi:[1,0,1] neg_lo:[1,0,0] neg_hi:[1,0,0]
	v_pk_mul_f32 v[78:79], v[50:51], v[66:67] op_sel_hi:[1,0]
	v_lshlrev_b32_e32 v104, 16, v74
	v_pk_fma_f32 v[72:73], v[78:79], v[70:71], v[72:73] op_sel_hi:[1,0,1] neg_lo:[1,0,0] neg_hi:[1,0,0]
	v_and_b32_e32 v105, 0xffff0000, v74
	v_mul_f32_e32 v78, v73, v73
	v_pk_fma_f32 v[84:85], v[72:73], v[72:73], v[78:79] op_sel_hi:[1,1,0]
	v_pk_mul_f32 v[78:79], v[48:49], v[66:67] op_sel_hi:[1,0]
	v_lshlrev_b32_e32 v74, 16, v75
	v_pk_fma_f32 v[78:79], v[78:79], v[70:71], v[102:103] op_sel_hi:[1,0,1] neg_lo:[1,0,0] neg_hi:[1,0,0]
	v_and_b32_e32 v75, 0xffff0000, v75
	v_mul_f32_e32 v80, v79, v79
	v_lshlrev_b32_e32 v136, 16, v81
	v_and_b32_e32 v137, 0xffff0000, v81
	v_lshlrev_b32_e32 v146, 16, v86
	v_and_b32_e32 v147, 0xffff0000, v86
	v_lshlrev_b32_e32 v148, 16, v87
	v_and_b32_e32 v149, 0xffff0000, v87
	v_pk_fma_f32 v[86:87], v[78:79], v[78:79], v[80:81] op_sel_hi:[1,1,0]
	v_pk_mul_f32 v[80:81], v[54:55], v[66:67] op_sel_hi:[1,0]
	v_lshlrev_b32_e32 v150, 16, v88
	v_pk_fma_f32 v[74:75], v[80:81], v[70:71], v[74:75] op_sel_hi:[1,0,1] neg_lo:[1,0,0] neg_hi:[1,0,0]
	v_and_b32_e32 v151, 0xffff0000, v88
	v_mul_f32_e32 v80, v75, v75
	v_lshlrev_b32_e32 v152, 16, v89
	v_and_b32_e32 v153, 0xffff0000, v89
	v_pk_fma_f32 v[88:89], v[74:75], v[74:75], v[80:81] op_sel_hi:[1,1,0]
	v_pk_mul_f32 v[80:81], v[52:53], v[66:67] op_sel_hi:[1,0]
	v_lshlrev_b32_e32 v138, 16, v82
	v_pk_fma_f32 v[80:81], v[80:81], v[70:71], v[104:105] op_sel_hi:[1,0,1] neg_lo:[1,0,0] neg_hi:[1,0,0]
	v_and_b32_e32 v139, 0xffff0000, v82
	v_mul_f32_e32 v82, v81, v81
	v_lshlrev_b32_e32 v106, 16, v76
	v_and_b32_e32 v107, 0xffff0000, v76
	v_lshlrev_b32_e32 v76, 16, v77
	v_and_b32_e32 v77, 0xffff0000, v77
	v_lshlrev_b32_e32 v140, 16, v83
	v_and_b32_e32 v141, 0xffff0000, v83
	v_lshlrev_b32_e32 v154, 16, v90
	v_and_b32_e32 v155, 0xffff0000, v90
	v_lshlrev_b32_e32 v156, 16, v91
	v_and_b32_e32 v157, 0xffff0000, v91
	v_pk_fma_f32 v[90:91], v[80:81], v[80:81], v[82:83] op_sel_hi:[1,1,0]
	v_pk_mul_f32 v[82:83], v[58:59], v[66:67] op_sel_hi:[1,0]
	v_lshlrev_b32_e32 v118, 16, v92
	v_pk_fma_f32 v[76:77], v[82:83], v[70:71], v[76:77] op_sel_hi:[1,0,1] neg_lo:[1,0,0] neg_hi:[1,0,0]
	v_pk_mul_f32 v[82:83], v[56:57], v[66:67] op_sel_hi:[1,0]
	v_and_b32_e32 v119, 0xffff0000, v92
	v_pk_fma_f32 v[82:83], v[82:83], v[70:71], v[106:107] op_sel_hi:[1,0,1] neg_lo:[1,0,0] neg_hi:[1,0,0]
	v_lshlrev_b32_e32 v158, 16, v93
	v_and_b32_e32 v159, 0xffff0000, v93
	v_lshlrev_b32_e32 v122, 16, v94
	v_and_b32_e32 v123, 0xffff0000, v94
	v_lshlrev_b32_e32 v112, 16, v95
	v_and_b32_e32 v113, 0xffff0000, v95
	v_pk_mul_f32 v[92:93], v[76:77], v[76:77]
	v_pk_mul_f32 v[94:95], v[82:83], v[82:83]
	v_mov_b32_e32 v91, v92
	v_mov_b32_e32 v89, v93
	v_mov_b32_e32 v87, v94
	v_mov_b32_e32 v85, v95
	v_pk_add_f32 v[88:89], v[90:91], v[88:89]
	v_pk_add_f32 v[84:85], v[86:87], v[84:85]
	v_lshlrev_b32_e32 v132, 16, v96
	v_pk_add_f32 v[84:85], v[84:85], v[88:89]
	v_and_b32_e32 v133, 0xffff0000, v96
	v_lshlrev_b32_e32 v124, 16, v97
	v_and_b32_e32 v125, 0xffff0000, v97
	v_pk_add_f32 v[96:97], v[84:85], v[84:85] op_sel:[0,1] op_sel_hi:[1,0]
	v_pk_mul_f32 v[84:85], v[62:63], v[66:67] op_sel_hi:[1,0]
	v_pk_mul_f32 v[86:87], v[60:61], v[66:67] op_sel_hi:[1,0]
	v_pk_fma_f32 v[84:85], v[84:85], v[70:71], v[110:111] op_sel_hi:[1,0,1] neg_lo:[1,0,0] neg_hi:[1,0,0]
	v_pk_fma_f32 v[90:91], v[86:87], v[70:71], v[108:109] op_sel_hi:[1,0,1] neg_lo:[1,0,0] neg_hi:[1,0,0]
	v_mov_b32_e32 v89, v85
	v_mov_b32_e32 v88, v91
	v_mov_b32_e32 v86, v90
	v_mov_b32_e32 v87, v84
	v_pk_mul_f32 v[88:89], v[88:89], v[88:89]
; __device__ __forceinline__ void attn_unit_a(FLAS unsigned char* lds, const Unit u) {
;     ...
;             for (int g = 0; g < 4; ++g) {
;                 const unsigned long long w = __hip_atomic_load((const unsigned long long*)(o1p + db * 32 + 8 * g), __ATOMIC_RELAXED, __HIP_MEMORY_SCOPE_AGENT);
;                 const unsigned w0 = (unsigned)w, w1 = (unsigned)(w >> 32);
;                 const float a0 = __builtin_bit_cast(float, w0 << 16), a1 = __builtin_bit_cast(float, w0 & 0xffff0000u), a2 = __builtin_bit_cast(float, w1 << 16), a3 = __builtin_bit_cast(float, w1 & 0xffff0000u);
;                 const float x0 = a0 - lam * (o[db][4 * g] * inv), x1 = a1 - lam * (o[db][4 * g + 1] * inv), x2 = a2 - lam * (o[db][4 * g + 2] * inv), x3 = a3 - lam * (o[db][4 * g + 3] * inv);
;                 o[db][4 * g] = x0; o[db][4 * g + 1] = x1; o[db][4 * g + 2] = x2; o[db][4 * g + 3] = x3; ss += (x0 * x0 + x1 * x1) + (x2 * x2 + x3 * x3); }
	v_lshlrev_b32_e32 v134, 16, v98
	v_pk_fma_f32 v[86:87], v[86:87], v[86:87], v[88:89]
	v_and_b32_e32 v135, 0xffff0000, v98
	v_lshlrev_b32_e32 v126, 16, v99
	v_and_b32_e32 v127, 0xffff0000, v99
	v_pk_add_f32 v[98:99], v[86:87], v[86:87] op_sel:[0,1] op_sel_hi:[1,0]
	v_pk_mul_f32 v[86:87], v[34:35], v[66:67] op_sel_hi:[1,0]
	v_lshlrev_b32_e32 v120, 16, v100
	v_pk_fma_f32 v[86:87], v[86:87], v[70:71], v[136:137] op_sel_hi:[1,0,1] neg_lo:[1,0,0] neg_hi:[1,0,0]
	v_and_b32_e32 v121, 0xffff0000, v100
	v_mul_f32_e32 v88, v87, v87
	v_lshlrev_b32_e32 v130, 16, v101
	v_and_b32_e32 v131, 0xffff0000, v101
	v_pk_fma_f32 v[100:101], v[86:87], v[86:87], v[88:89] op_sel_hi:[1,1,0]
	v_pk_mul_f32 v[88:89], v[32:33], v[66:67] op_sel_hi:[1,0]
	v_pk_mul_f32 v[94:95], v[36:37], v[66:67] op_sel_hi:[1,0]
	v_pk_fma_f32 v[92:93], v[88:89], v[70:71], v[116:117] op_sel_hi:[1,0,1] neg_lo:[1,0,0] neg_hi:[1,0,0]
	v_pk_fma_f32 v[94:95], v[94:95], v[70:71], v[138:139] op_sel_hi:[1,0,1] neg_lo:[1,0,0] neg_hi:[1,0,0]
	v_mul_f32_e32 v88, v93, v93
	v_pk_fma_f32 v[102:103], v[92:93], v[92:93], v[88:89] op_sel_hi:[1,1,0]
	v_pk_mul_f32 v[88:89], v[38:39], v[66:67] op_sel_hi:[1,0]
	v_pk_mul_f32 v[106:107], v[94:95], v[94:95]
	v_pk_fma_f32 v[88:89], v[88:89], v[70:71], v[140:141] op_sel_hi:[1,0,1] neg_lo:[1,0,0] neg_hi:[1,0,0]
	v_mov_b32_e32 v97, v106
	v_pk_mul_f32 v[104:105], v[88:89], v[88:89]
	v_mov_b32_e32 v99, v107
	v_mov_b32_e32 v103, v104
	v_mov_b32_e32 v101, v105
	v_pk_add_f32 v[100:101], v[102:103], v[100:101]
	v_pk_add_f32 v[96:97], v[96:97], v[98:99]
	v_pk_mul_f32 v[98:99], v[40:41], v[66:67] op_sel_hi:[1,0]
	v_pk_add_f32 v[96:97], v[96:97], v[100:101]
	v_pk_fma_f32 v[102:103], v[98:99], v[70:71], v[142:143] op_sel_hi:[1,0,1] neg_lo:[1,0,0] neg_hi:[1,0,0]
	v_pk_add_f32 v[108:109], v[96:97], v[96:97] op_sel:[0,1] op_sel_hi:[1,0]
	v_pk_mul_f32 v[96:97], v[42:43], v[66:67] op_sel_hi:[1,0]
	v_mov_b32_e32 v100, v103
	v_pk_fma_f32 v[96:97], v[96:97], v[70:71], v[144:145] op_sel_hi:[1,0,1] neg_lo:[1,0,0] neg_hi:[1,0,0]
	v_mov_b32_e32 v98, v102
	v_mov_b32_e32 v101, v97
	v_mov_b32_e32 v99, v96
	v_pk_mul_f32 v[100:101], v[100:101], v[100:101]
	v_pk_mul_f32 v[104:105], v[16:17], v[66:67] op_sel_hi:[1,0]
	v_pk_fma_f32 v[98:99], v[98:99], v[98:99], v[100:101]
	v_pk_fma_f32 v[104:105], v[104:105], v[70:71], v[150:151] op_sel_hi:[1,0,1] neg_lo:[1,0,0] neg_hi:[1,0,0]
	v_pk_add_f32 v[110:111], v[98:99], v[98:99] op_sel:[0,1] op_sel_hi:[1,0]
	v_pk_mul_f32 v[98:99], v[46:47], v[66:67] op_sel_hi:[1,0]
	v_pk_mul_f32 v[140:141], v[104:105], v[104:105]
	v_pk_fma_f32 v[98:99], v[98:99], v[70:71], v[148:149] op_sel_hi:[1,0,1] neg_lo:[1,0,0] neg_hi:[1,0,0]
	v_mov_b32_e32 v109, v140
	v_mul_f32_e32 v100, v99, v99
	v_pk_fma_f32 v[116:117], v[98:99], v[98:99], v[100:101] op_sel_hi:[1,1,0]
	v_pk_mul_f32 v[100:101], v[44:45], v[66:67] op_sel_hi:[1,0]
	v_mov_b32_e32 v111, v141
	v_pk_fma_f32 v[106:107], v[100:101], v[70:71], v[146:147] op_sel_hi:[1,0,1] neg_lo:[1,0,0] neg_hi:[1,0,0]
	v_pk_add_f32 v[108:109], v[108:109], v[110:111]
	v_mul_f32_e32 v100, v107, v107
	v_pk_fma_f32 v[136:137], v[106:107], v[106:107], v[100:101] op_sel_hi:[1,1,0]
	v_pk_mul_f32 v[100:101], v[18:19], v[66:67] op_sel_hi:[1,0]
	v_pk_mul_f32 v[110:111], v[20:21], v[66:67] op_sel_hi:[1,0]
	v_pk_fma_f32 v[100:101], v[100:101], v[70:71], v[152:153] op_sel_hi:[1,0,1] neg_lo:[1,0,0] neg_hi:[1,0,0]
	v_pk_mul_f32 v[146:147], v[28:29], v[66:67] op_sel_hi:[1,0]
	v_pk_mul_f32 v[138:139], v[100:101], v[100:101]
	v_pk_mul_f32 v[142:143], v[24:25], v[66:67] op_sel_hi:[1,0]
	v_mov_b32_e32 v137, v138
	v_mov_b32_e32 v117, v139
	v_pk_add_f32 v[116:117], v[136:137], v[116:117]
	v_pk_fma_f32 v[122:123], v[146:147], v[70:71], v[122:123] op_sel_hi:[1,0,1] neg_lo:[1,0,0] neg_hi:[1,0,0]
	v_pk_add_f32 v[108:109], v[108:109], v[116:117]
	v_pk_fma_f32 v[116:117], v[110:111], v[70:71], v[154:155] op_sel_hi:[1,0,1] neg_lo:[1,0,0] neg_hi:[1,0,0]
	v_pk_add_f32 v[136:137], v[108:109], v[108:109] op_sel:[0,1] op_sel_hi:[1,0]
	v_pk_mul_f32 v[108:109], v[22:23], v[66:67] op_sel_hi:[1,0]
	v_mov_b32_e32 v138, v117
	v_pk_fma_f32 v[108:109], v[108:109], v[70:71], v[156:157] op_sel_hi:[1,0,1] neg_lo:[1,0,0] neg_hi:[1,0,0]
	v_mov_b32_e32 v110, v116
	v_mov_b32_e32 v139, v109
	v_mov_b32_e32 v111, v108
	v_pk_mul_f32 v[138:139], v[138:139], v[138:139]
	v_pk_fma_f32 v[118:119], v[142:143], v[70:71], v[118:119] op_sel_hi:[1,0,1] neg_lo:[1,0,0] neg_hi:[1,0,0]
	v_pk_fma_f32 v[110:111], v[110:111], v[110:111], v[138:139]
	v_pk_mul_f32 v[144:145], v[30:31], v[66:67] op_sel_hi:[1,0]
	v_pk_add_f32 v[138:139], v[110:111], v[110:111] op_sel:[0,1] op_sel_hi:[1,0]
	v_pk_mul_f32 v[110:111], v[26:27], v[66:67] op_sel_hi:[1,0]
	v_pk_mul_f32 v[146:147], v[122:123], v[122:123]
	v_pk_fma_f32 v[110:111], v[110:111], v[70:71], v[158:159] op_sel_hi:[1,0,1] neg_lo:[1,0,0] neg_hi:[1,0,0]
	v_mul_f32_e32 v142, v119, v119
	v_mul_f32_e32 v140, v111, v111
	v_pk_fma_f32 v[112:113], v[144:145], v[70:71], v[112:113] op_sel_hi:[1,0,1] neg_lo:[1,0,0] neg_hi:[1,0,0]
	v_mov_b32_e32 v137, v146
	v_mov_b32_e32 v139, v147
	v_pk_fma_f32 v[140:141], v[110:111], v[110:111], v[140:141] op_sel_hi:[1,1,0]
	v_pk_fma_f32 v[142:143], v[118:119], v[118:119], v[142:143] op_sel_hi:[1,1,0]
	v_pk_mul_f32 v[144:145], v[112:113], v[112:113]
	v_pk_add_f32 v[136:137], v[136:137], v[138:139]
	v_pk_mul_f32 v[138:139], v[2:3], v[66:67] op_sel_hi:[1,0]
	v_mov_b32_e32 v143, v144
	v_mov_b32_e32 v141, v145
	v_pk_fma_f32 v[124:125], v[138:139], v[70:71], v[124:125] op_sel_hi:[1,0,1] neg_lo:[1,0,0] neg_hi:[1,0,0]
	v_pk_mul_f32 v[138:139], v[0:1], v[66:67] op_sel_hi:[1,0]
	v_pk_add_f32 v[140:141], v[142:143], v[140:141]
; __device__ __forceinline__ unsigned cvtpk(float lo, float hi) { f32x2_t v = {lo, hi}; bf16x2_t b = __builtin_convertvector(v, bf16x2_t); return __builtin_bit_cast(unsigned, b); }
; __device__ __forceinline__ float xhalf_sum(float m) { unsigned a = __builtin_bit_cast(unsigned, m), b = a; xswap(a, b); return __builtin_bit_cast(float, a) + __builtin_bit_cast(float, b); }
; __device__ __forceinline__ void attn_unit_a(FLAS unsigned char* lds, const Unit u) {
;     ...
;                 const float x0 = a0 - lam * (o[db][4 * g] * inv), x1 = a1 - lam * (o[db][4 * g + 1] * inv), x2 = a2 - lam * (o[db][4 * g + 2] * inv), x3 = a3 - lam * (o[db][4 * g + 3] * inv);
;                 o[db][4 * g] = x0; o[db][4 * g + 1] = x1; o[db][4 * g + 2] = x2; o[db][4 * g + 3] = x3; ss += (x0 * x0 + x1 * x1) + (x2 * x2 + x3 * x3); }
;         const float rr = 1.0f / sqrtf(xhalf_sum(ss) * (1.f / 128.f) + 1e-6f) * gsc;
; #pragma unroll
;         for (int db = 0; db < NDB; ++db)
; #pragma unroll
;             for (int g = 0; g < 4; ++g) { const float* gp = u.sgain + db * 32 + 8 * g + 4 * hi; u32x2 w;
;                 w.x = cvtpk(o[db][4 * g] * rr * gp[0], o[db][4 * g + 1] * rr * gp[1]); w.y = cvtpk(o[db][4 * g + 2] * rr * gp[2], o[db][4 * g + 3] * rr * gp[3]);
;                 *(u32x2*)(op + db * 32 + 8 * g) = w; }
	v_pk_fma_f32 v[132:133], v[138:139], v[70:71], v[132:133] op_sel_hi:[1,0,1] neg_lo:[1,0,0] neg_hi:[1,0,0]
	v_pk_mul_f32 v[144:145], v[10:11], v[66:67] op_sel_hi:[1,0]
	v_pk_mul_f32 v[146:147], v[8:9], v[66:67] op_sel_hi:[1,0]
	v_pk_add_f32 v[136:137], v[136:137], v[140:141]
	v_mov_b32_e32 v140, v133
	v_mov_b32_e32 v141, v125
	v_pk_fma_f32 v[130:131], v[144:145], v[70:71], v[130:131] op_sel_hi:[1,0,1] neg_lo:[1,0,0] neg_hi:[1,0,0]
	v_pk_fma_f32 v[120:121], v[146:147], v[70:71], v[120:121] op_sel_hi:[1,0,1] neg_lo:[1,0,0] neg_hi:[1,0,0]
	v_mov_b32_e32 v138, v132
	v_mov_b32_e32 v139, v124
	v_pk_mul_f32 v[140:141], v[140:141], v[140:141]
	v_mul_f32_e32 v144, v131, v131
	v_mul_f32_e32 v146, v121, v121
	v_pk_mul_f32 v[128:129], v[68:69], v[68:69]
	v_pk_fma_f32 v[138:139], v[138:139], v[138:139], v[140:141]
	v_pk_mul_f32 v[140:141], v[6:7], v[66:67] op_sel_hi:[1,0]
	v_pk_mul_f32 v[142:143], v[4:5], v[66:67] op_sel_hi:[1,0]
	v_pk_fma_f32 v[144:145], v[130:131], v[130:131], v[144:145] op_sel_hi:[1,1,0]
	v_pk_fma_f32 v[146:147], v[120:121], v[120:121], v[146:147] op_sel_hi:[1,1,0]
	v_pk_fma_f32 v[126:127], v[140:141], v[70:71], v[126:127] op_sel_hi:[1,0,1] neg_lo:[1,0,0] neg_hi:[1,0,0]
	v_pk_fma_f32 v[134:135], v[142:143], v[70:71], v[134:135] op_sel_hi:[1,0,1] neg_lo:[1,0,0] neg_hi:[1,0,0]
	v_mov_b32_e32 v147, v128
	v_mov_b32_e32 v145, v129
	v_mul_f32_e32 v140, v127, v127
	v_mul_f32_e32 v142, v135, v135
	v_pk_add_f32 v[128:129], v[146:147], v[144:145]
	v_pk_mul_f32 v[144:145], v[12:13], v[66:67] op_sel_hi:[1,0]
	v_pk_add_f32 v[136:137], v[136:137], v[136:137] op_sel:[0,1] op_sel_hi:[1,0]
	v_pk_add_f32 v[138:139], v[138:139], v[138:139] op_sel:[0,1] op_sel_hi:[1,0]
	v_pk_fma_f32 v[140:141], v[126:127], v[126:127], v[140:141] op_sel_hi:[1,1,0]
	v_pk_fma_f32 v[142:143], v[134:135], v[134:135], v[142:143] op_sel_hi:[1,1,0]
	v_pk_fma_f32 v[70:71], v[144:145], v[70:71], v[114:115] op_sel_hi:[1,0,1] neg_lo:[1,0,0] neg_hi:[1,0,0]
	v_pk_add_f32 v[114:115], v[136:137], v[138:139]
	v_pk_mul_f32 v[136:137], v[70:71], v[70:71]
	v_pk_add_f32 v[138:139], v[142:143], v[140:141]
	v_mov_b32_e32 v115, v136
	v_mov_b32_e32 v139, v137
	v_pk_add_f32 v[114:115], v[114:115], v[138:139]
	s_nop 0
	v_pk_add_f32 v[114:115], v[114:115], v[128:129]
	s_nop 0
	v_pk_add_f32 v[114:115], v[114:115], v[114:115] op_sel:[0,1] op_sel_hi:[1,0]
	s_nop 0
	v_mov_b32_e32 v115, v114
	s_nop 1
	v_permlane32_swap_b32 v115, v114
	s_nop 1
	global_load_dwordx4 v[136:139], v67, s[8:9]
	v_add_f32_e32 v114, v115, v114
	v_fmamk_f32 v114, v114, 0x3c000000, v240
	v_mul_f32_e32 v115, 0x4f800000, v114
	v_cmp_gt_f32_e32 vcc, s35, v114
	s_nop 1
	v_cndmask_b32_e32 v114, v114, v115, vcc
	v_sqrt_f32_e32 v115, v114
	s_nop 0
	v_add_u32_e32 v128, -1, v115
	v_fma_f32 v129, -v128, v115, v114
	v_cmp_ge_f32_e64 s[4:5], 0, v129
	v_add_u32_e32 v129, 1, v115
	s_nop 0
	v_cndmask_b32_e64 v128, v115, v128, s[4:5]
	v_fma_f32 v115, -v129, v115, v114
	v_cmp_lt_f32_e64 s[4:5], 0, v115
	s_nop 1
	v_cndmask_b32_e64 v115, v128, v129, s[4:5]
	v_mul_f32_e32 v128, 0x37800000, v115
	v_cndmask_b32_e32 v115, v115, v128, vcc
	v_cmp_class_f32_e32 vcc, v114, v244
	s_mov_b64 s[4:5], 0
	s_nop 0
	v_cndmask_b32_e32 v114, v115, v114, vcc
	v_div_scale_f32 v115, s[0:1], v114, v114, 1.0
	v_rcp_f32_e32 v128, v115
	s_nop 0
	v_fma_f32 v129, -v115, v128, 1.0
	v_fmac_f32_e32 v128, v129, v128
	v_div_scale_f32 v129, vcc, 1.0, v114, 1.0
	v_mul_f32_e32 v140, v129, v128
	v_fma_f32 v141, -v115, v140, v129
	v_fmac_f32_e32 v140, v141, v128
	v_fma_f32 v115, -v115, v140, v129
	v_div_fmas_f32 v115, v115, v128, v140
	v_div_fixup_f32 v114, v115, v114, 1.0
	v_mul_f32_e32 v114, v237, v114
	v_pk_mul_f32 v[78:79], v[78:79], v[114:115] op_sel_hi:[1,0]
	v_pk_mul_f32 v[72:73], v[72:73], v[114:115] op_sel_hi:[1,0]
	v_pk_mul_f32 v[74:75], v[74:75], v[114:115] op_sel_hi:[1,0]
	v_pk_mul_f32 v[76:77], v[76:77], v[114:115] op_sel_hi:[1,0]
	v_pk_mul_f32 v[70:71], v[70:71], v[114:115] op_sel_hi:[1,0]
	v_pk_mul_f32 v[68:69], v[68:69], v[114:115] op_sel_hi:[1,0]
	s_waitcnt vmcnt(0)
	v_pk_mul_f32 v[78:79], v[136:137], v[78:79]
	v_pk_mul_f32 v[72:73], v[138:139], v[72:73]
	v_cvt_pk_bf16_f32 v78, v78, v79
	v_cvt_pk_bf16_f32 v79, v72, v73
	global_store_dwordx2 v[64:65], v[78:79], off
	global_load_dwordx4 v[136:139], v67, s[8:9] offset:32
	v_pk_mul_f32 v[72:73], v[80:81], v[114:115] op_sel_hi:[1,0]
	v_pk_mul_f32 v[78:79], v[82:83], v[114:115] op_sel_hi:[1,0]
	s_waitcnt vmcnt(0)
	v_pk_mul_f32 v[72:73], v[136:137], v[72:73]
	v_pk_mul_f32 v[74:75], v[138:139], v[74:75]
	v_cvt_pk_bf16_f32 v72, v72, v73
	v_cvt_pk_bf16_f32 v73, v74, v75
	global_store_dwordx2 v[64:65], v[72:73], off offset:16
	global_load_dwordx4 v[72:75], v67, s[8:9] offset:64
	s_waitcnt vmcnt(0)
	v_pk_mul_f32 v[72:73], v[78:79], v[72:73]
	v_pk_mul_f32 v[74:75], v[76:77], v[74:75]
	v_cvt_pk_bf16_f32 v72, v72, v73
	v_cvt_pk_bf16_f32 v73, v74, v75
	global_store_dwordx2 v[64:65], v[72:73], off offset:32
	global_load_dwordx4 v[72:75], v67, s[8:9] offset:96
	v_pk_mul_f32 v[76:77], v[90:91], v[114:115] op_sel_hi:[1,0]
	v_pk_mul_f32 v[78:79], v[84:85], v[114:115] op_sel_hi:[1,0]
	s_waitcnt vmcnt(0)
; __device__ __forceinline__ unsigned cvtpk(float lo, float hi) { f32x2_t v = {lo, hi}; bf16x2_t b = __builtin_convertvector(v, bf16x2_t); return __builtin_bit_cast(unsigned, b); }
; __device__ __forceinline__ void attn_unit_a(FLAS unsigned char* lds, const Unit u) {
;     ...
; #pragma unroll
;         for (int db = 0; db < NDB; ++db)
; #pragma unroll
;             for (int g = 0; g < 4; ++g) { const float* gp = u.sgain + db * 32 + 8 * g + 4 * hi; u32x2 w;
;                 w.x = cvtpk(o[db][4 * g] * rr * gp[0], o[db][4 * g + 1] * rr * gp[1]); w.y = cvtpk(o[db][4 * g + 2] * rr * gp[2], o[db][4 * g + 3] * rr * gp[3]);
;                 *(u32x2*)(op + db * 32 + 8 * g) = w; }
	v_pk_mul_f32 v[72:73], v[76:77], v[72:73]
	v_pk_mul_f32 v[74:75], v[78:79], v[74:75]
	v_cvt_pk_bf16_f32 v72, v72, v73
	v_cvt_pk_bf16_f32 v73, v74, v75
	global_store_dwordx2 v[64:65], v[72:73], off offset:48
	global_load_dwordx4 v[72:75], v67, s[8:9] offset:128
	v_pk_mul_f32 v[76:77], v[92:93], v[114:115] op_sel_hi:[1,0]
	v_pk_mul_f32 v[78:79], v[86:87], v[114:115] op_sel_hi:[1,0]
	s_waitcnt vmcnt(0)
	v_pk_mul_f32 v[72:73], v[76:77], v[72:73]
	v_pk_mul_f32 v[74:75], v[78:79], v[74:75]
	v_cvt_pk_bf16_f32 v72, v72, v73
	v_cvt_pk_bf16_f32 v73, v74, v75
	global_store_dwordx2 v[64:65], v[72:73], off offset:64
	global_load_dwordx4 v[72:75], v67, s[8:9] offset:160
	v_pk_mul_f32 v[76:77], v[94:95], v[114:115] op_sel_hi:[1,0]
	v_pk_mul_f32 v[78:79], v[88:89], v[114:115] op_sel_hi:[1,0]
	s_waitcnt vmcnt(0)
	v_pk_mul_f32 v[72:73], v[76:77], v[72:73]
	v_pk_mul_f32 v[74:75], v[78:79], v[74:75]
	v_cvt_pk_bf16_f32 v72, v72, v73
	v_cvt_pk_bf16_f32 v73, v74, v75
	global_store_dwordx2 v[64:65], v[72:73], off offset:80
	global_load_dwordx4 v[72:75], v67, s[8:9] offset:192
	v_pk_mul_f32 v[76:77], v[102:103], v[114:115] op_sel_hi:[1,0]
	v_pk_mul_f32 v[78:79], v[96:97], v[114:115] op_sel_hi:[1,0]
	s_waitcnt vmcnt(0)
	v_pk_mul_f32 v[72:73], v[76:77], v[72:73]
	v_pk_mul_f32 v[74:75], v[78:79], v[74:75]
	v_cvt_pk_bf16_f32 v72, v72, v73
	v_cvt_pk_bf16_f32 v73, v74, v75
	global_store_dwordx2 v[64:65], v[72:73], off offset:96
	global_load_dwordx4 v[72:75], v67, s[8:9] offset:224
	v_pk_mul_f32 v[76:77], v[106:107], v[114:115] op_sel_hi:[1,0]
	v_pk_mul_f32 v[78:79], v[98:99], v[114:115] op_sel_hi:[1,0]
	s_waitcnt vmcnt(0)
	v_pk_mul_f32 v[72:73], v[76:77], v[72:73]
	v_pk_mul_f32 v[74:75], v[78:79], v[74:75]
	v_cvt_pk_bf16_f32 v72, v72, v73
	v_cvt_pk_bf16_f32 v73, v74, v75
	global_store_dwordx2 v[64:65], v[72:73], off offset:112
	global_load_dwordx4 v[72:75], v67, s[8:9] offset:256
	v_pk_mul_f32 v[76:77], v[104:105], v[114:115] op_sel_hi:[1,0]
	v_pk_mul_f32 v[78:79], v[100:101], v[114:115] op_sel_hi:[1,0]
	s_waitcnt vmcnt(0)
	v_pk_mul_f32 v[72:73], v[76:77], v[72:73]
	v_pk_mul_f32 v[74:75], v[78:79], v[74:75]
	v_cvt_pk_bf16_f32 v72, v72, v73
	v_cvt_pk_bf16_f32 v73, v74, v75
	global_store_dwordx2 v[64:65], v[72:73], off offset:128
	global_load_dwordx4 v[72:75], v67, s[8:9] offset:288
	v_pk_mul_f32 v[76:77], v[116:117], v[114:115] op_sel_hi:[1,0]
	v_pk_mul_f32 v[78:79], v[108:109], v[114:115] op_sel_hi:[1,0]
	s_waitcnt vmcnt(0)
	v_pk_mul_f32 v[72:73], v[76:77], v[72:73]
	v_pk_mul_f32 v[74:75], v[78:79], v[74:75]
	v_cvt_pk_bf16_f32 v72, v72, v73
	v_cvt_pk_bf16_f32 v73, v74, v75
	global_store_dwordx2 v[64:65], v[72:73], off offset:144
	global_load_dwordx4 v[72:75], v67, s[8:9] offset:320
	v_pk_mul_f32 v[76:77], v[118:119], v[114:115] op_sel_hi:[1,0]
	v_pk_mul_f32 v[78:79], v[110:111], v[114:115] op_sel_hi:[1,0]
	s_waitcnt vmcnt(0)
	v_pk_mul_f32 v[72:73], v[76:77], v[72:73]
	v_pk_mul_f32 v[74:75], v[78:79], v[74:75]
	v_cvt_pk_bf16_f32 v72, v72, v73
	v_cvt_pk_bf16_f32 v73, v74, v75
	global_store_dwordx2 v[64:65], v[72:73], off offset:160
	global_load_dwordx4 v[72:75], v67, s[8:9] offset:352
	v_pk_mul_f32 v[76:77], v[122:123], v[114:115] op_sel_hi:[1,0]
	v_pk_mul_f32 v[78:79], v[112:113], v[114:115] op_sel_hi:[1,0]
	s_waitcnt vmcnt(0)
	v_pk_mul_f32 v[72:73], v[76:77], v[72:73]
	v_pk_mul_f32 v[74:75], v[78:79], v[74:75]
	v_cvt_pk_bf16_f32 v72, v72, v73
	v_cvt_pk_bf16_f32 v73, v74, v75
	global_store_dwordx2 v[64:65], v[72:73], off offset:176
	global_load_dwordx4 v[72:75], v67, s[8:9] offset:384
	v_pk_mul_f32 v[76:77], v[132:133], v[114:115] op_sel_hi:[1,0]
	v_pk_mul_f32 v[78:79], v[124:125], v[114:115] op_sel_hi:[1,0]
	s_waitcnt vmcnt(0)
	v_pk_mul_f32 v[72:73], v[76:77], v[72:73]
	v_pk_mul_f32 v[74:75], v[78:79], v[74:75]
	v_cvt_pk_bf16_f32 v72, v72, v73
	v_cvt_pk_bf16_f32 v73, v74, v75
	global_store_dwordx2 v[64:65], v[72:73], off offset:192
	global_load_dwordx4 v[72:75], v67, s[8:9] offset:416
	v_pk_mul_f32 v[76:77], v[134:135], v[114:115] op_sel_hi:[1,0]
	v_pk_mul_f32 v[78:79], v[126:127], v[114:115] op_sel_hi:[1,0]
	s_waitcnt vmcnt(0)
	v_pk_mul_f32 v[72:73], v[76:77], v[72:73]
	v_pk_mul_f32 v[74:75], v[78:79], v[74:75]
	v_cvt_pk_bf16_f32 v72, v72, v73
	v_cvt_pk_bf16_f32 v73, v74, v75
	global_store_dwordx2 v[64:65], v[72:73], off offset:208
	global_load_dwordx4 v[72:75], v67, s[8:9] offset:448
	v_pk_mul_f32 v[76:77], v[120:121], v[114:115] op_sel_hi:[1,0]
	v_pk_mul_f32 v[78:79], v[130:131], v[114:115] op_sel_hi:[1,0]
	s_waitcnt vmcnt(0)
	v_pk_mul_f32 v[72:73], v[76:77], v[72:73]
	v_pk_mul_f32 v[74:75], v[78:79], v[74:75]
	v_cvt_pk_bf16_f32 v72, v72, v73
	v_cvt_pk_bf16_f32 v73, v74, v75
	global_store_dwordx2 v[64:65], v[72:73], off offset:224
	global_load_dwordx4 v[72:75], v67, s[8:9] offset:480
	s_waitcnt vmcnt(0)
	v_pk_mul_f32 v[72:73], v[70:71], v[72:73]
	v_pk_mul_f32 v[70:71], v[68:69], v[74:75]
	v_cvt_pk_bf16_f32 v68, v72, v73
